# scan: prefetch distance 2 steps instead of 3 (smaller start-up burst and less over-read at the end of the unit)
# speedup vs baseline: 1.0108x; 1.0002x over previous
.LBB0_652:
	s_andn2_b64 vcc, exec, s[0:1]
	s_cbranch_vccnz .LBB0_704
	v_and_b32_e32 v14, 63, v206
	v_lshrrev_b32_e32 v15, 6, v206
	v_and_b32_e32 v64, 15, v14
	v_readfirstlane_b32 s11, v15
	v_lshrrev_b32_e32 v65, 4, v14
	v_lshlrev_b32_e32 v66, 2, v206
	ds_write_b32 v66, v0
	ds_write_b32 v66, v0 offset:2048
	ds_write_b32 v66, v0 offset:4096
	ds_write_b32 v66, v0 offset:6144
	ds_write_b32 v66, v0 offset:8192
	s_and_b32 s12, s11, 3
	s_and_b32 s13, s72, 7
	s_lshr_b32 s14, s72, 5
	s_bfe_u32 s15, s72, 0x20003
	s_lshl_b32 s16, s14, 3
	s_add_u32 s16, s16, s13
	s_lshl_b32 s17, s16, 21
	s_mov_b32 s18, 0x13800000
	s_cmp_lt_u32 s11, 4
	s_cselect_b32 s18, 0x11800000, s18
	s_add_u32 s18, s18, s17
	s_lshl_b32 s19, s12, 12
	s_add_u32 s18, s18, s19
	s_add_u32 s0, s70, s18
	s_addc_u32 s1, s71, 0
	s_lshl_b32 s19, s11, 11
	s_add_u32 s18, s17, s19
	s_add_u32 s18, s18, 0x15800000
	s_add_u32 s4, s70, s18
	s_addc_u32 s5, s71, 0
	s_lshl_b32 s18, s16, 9
	s_add_u32 s18, s18, 0x11500000
	s_add_u32 s6, s70, s18
	s_addc_u32 s7, s71, 0
	s_lshl_b32 s18, s15, 12
	s_lshl_b32 s19, s12, 9
	s_add_u32 s18, s18, s19
	s_add_u32 s18, s18, s17
	s_add_u32 s18, s18, 0x17800000
	s_lshl_b32 s19, s16, 20
	s_lshl_b32 s20, s12, 11
	s_add_u32 s19, s19, s20
	s_add_u32 s19, s19, 0x19800000
	s_cmp_lt_u32 s11, 4
	s_cselect_b32 s18, s18, s19
	s_add_u32 s2, s70, s18
	s_addc_u32 s3, s71, 0
	s_lshl_b32 s18, s14, 24
	s_lshl_b32 s19, s12, 15
	s_add_u32 s18, s18, s19
	s_lshl_b32 s19, s13, 8
	s_add_u32 s18, s18, s19
	s_lshl_b32 s19, s15, 6
	s_add_u32 s18, s18, s19
	s_add_u32 s18, s18, 0xb400000
	s_add_u32 s8, s70, s18
	s_addc_u32 s9, s71, 0
	v_lshlrev_b32_e32 v1, 4, v14
	v_mov_b32_e32 v3, 0
	v_mul_u32_u24_e32 v8, 0x110, v64
	v_mul_u32_u24_e32 v9, 0x90, v64
	v_lshl_add_u32 v11, v65, 3, v8
	v_lshl_add_u32 v10, v65, 3, v9
	v_lshl_add_u32 v8, v65, 4, v8
	v_lshl_add_u32 v9, v65, 4, v9
	s_lshl_b32 s18, s11, 5
	v_add_u32_e32 v11, s18, v11
	s_lshl_b32 s18, s12, 5
	v_add_u32_e32 v10, s18, v10
	s_mul_i32 s18, s12, 0x500
	s_add_u32 s18, s18, 0x5800
	v_mul_u32_u24_e32 v13, 0x140, v65
	v_lshl_add_u32 v13, v64, 1, v13
	v_add_u32_e32 v13, s18, v13
	v_lshrrev_b32_e32 v67, 2, v14
	v_and_b32_e32 v68, 3, v14
	v_mul_u32_u24_e32 v172, 0x50, v67
	v_lshl_add_u32 v172, v68, 4, v172
	v_add_u32_e32 v172, s18, v172
	v_lshlrev_b32_e32 v12, 11, v67
	v_lshl_add_u32 v12, v68, 4, v12
	v_mov_b32_e32 v16, 0
	v_mov_b32_e32 v17, 0
	v_mov_b32_e32 v18, 0
	v_mov_b32_e32 v19, 0
	v_mov_b32_e32 v20, 0
	v_mov_b32_e32 v21, 0
	v_mov_b32_e32 v22, 0
	v_mov_b32_e32 v23, 0
	s_cmp_lt_u32 s11, 4
	s_waitcnt lgkmcnt(0)
	s_barrier
	s_cbranch_scc0 .Lscan_O_path
	v_lshlrev_b32_e32 v2, 3, v14
	global_load_dwordx4 v[72:75], v1, s[0:1]
	global_load_dwordx4 v[76:79], v1, s[0:1] offset:1024
	global_load_dwordx4 v[80:83], v1, s[0:1] offset:2048
	global_load_dwordx4 v[84:87], v1, s[0:1] offset:3072
	global_load_dwordx2 v[88:89], v2, s[2:3]
	global_load_dwordx2 v[90:91], v2, s[2:3] offset:2048
	global_load_dwordx4 v[96:99], v1, s[4:5]
	global_load_dwordx4 v[100:103], v1, s[4:5] offset:1024
	global_load_dword v184, v3, s[6:7]
	v_add_u32_e32 v1, 0x4000, v1
	v_add_u32_e32 v2, 0x4000, v2
	v_add_u32_e32 v3, 4, v3
	global_load_dwordx4 v[104:107], v1, s[0:1]
	global_load_dwordx4 v[108:111], v1, s[0:1] offset:1024
	global_load_dwordx4 v[112:115], v1, s[0:1] offset:2048
	global_load_dwordx4 v[116:119], v1, s[0:1] offset:3072
	global_load_dwordx2 v[120:121], v2, s[2:3]
	global_load_dwordx2 v[122:123], v2, s[2:3] offset:2048
	global_load_dwordx4 v[128:131], v1, s[4:5]
	global_load_dwordx4 v[132:135], v1, s[4:5] offset:1024
	global_load_dword v185, v3, s[6:7]
	v_add_u32_e32 v1, 0x4000, v1
	v_add_u32_e32 v2, 0x4000, v2
	v_add_u32_e32 v3, 4, v3
	s_waitcnt vmcnt(0)
	s_movk_i32 s10, 32
.Lscan_V_loop:
	s_waitcnt vmcnt(14)
	ds_read_b128 v[32:35], v8 offset:0
	ds_read_b128 v[36:39], v8 offset:4352
	ds_read_b128 v[40:43], v8 offset:64
	ds_read_b128 v[44:47], v8 offset:4416
	ds_read_b128 v[48:51], v8 offset:128
	ds_read_b128 v[52:55], v8 offset:4480
	ds_read_b128 v[56:59], v8 offset:192
	ds_read_b128 v[60:63], v8 offset:4544
	global_load_dwordx4 v[136:139], v1, s[0:1]
	global_load_dwordx4 v[140:143], v1, s[0:1] offset:1024
	s_waitcnt vmcnt(11)
	v_mul_f32_e32 v16, v184, v16
	v_mul_f32_e32 v17, v184, v17
	v_mul_f32_e32 v18, v184, v18
	v_mul_f32_e32 v19, v184, v19
	global_load_dwordx4 v[144:147], v1, s[0:1] offset:2048
	v_mul_f32_e32 v20, v184, v20
	v_mul_f32_e32 v21, v184, v21
	v_mul_f32_e32 v22, v184, v22
	v_mul_f32_e32 v23, v184, v23
	v_lshlrev_b32_e32 v64, 16, v88
	v_and_b32_e32 v65, 0xffff0000, v88
	v_lshlrev_b32_e32 v66, 16, v89
	v_and_b32_e32 v67, 0xffff0000, v89
	v_lshlrev_b32_e32 v68, 16, v90
	v_and_b32_e32 v69, 0xffff0000, v90
	v_lshlrev_b32_e32 v70, 16, v91
	v_and_b32_e32 v71, 0xffff0000, v91
	global_load_dwordx4 v[148:151], v1, s[0:1] offset:3072
	s_waitcnt lgkmcnt(6)
	v_mfma_f32_16x16x32_bf16 v[24:27], v[72:75], v[32:35], 0
	v_mfma_f32_16x16x32_bf16 v[28:31], v[72:75], v[36:39], 0
	global_load_dwordx2 v[188:189], v2, s[2:3]
	s_waitcnt lgkmcnt(4)
	v_mfma_f32_16x16x32_bf16 v[24:27], v[76:79], v[40:43], v[24:27]
	v_mfma_f32_16x16x32_bf16 v[28:31], v[76:79], v[44:47], v[28:31]
	global_load_dwordx2 v[190:191], v2, s[2:3] offset:2048
	s_waitcnt lgkmcnt(2)
	v_mfma_f32_16x16x32_bf16 v[24:27], v[80:83], v[48:51], v[24:27]
	v_mfma_f32_16x16x32_bf16 v[28:31], v[80:83], v[52:55], v[28:31]
	global_load_dwordx4 v[196:199], v1, s[4:5]
	s_waitcnt lgkmcnt(0)
	v_mfma_f32_16x16x32_bf16 v[24:27], v[84:87], v[56:59], v[24:27]
	v_mfma_f32_16x16x32_bf16 v[28:31], v[84:87], v[60:63], v[28:31]
	global_load_dwordx4 v[200:203], v1, s[4:5] offset:1024
	global_load_dword v186, v3, s[6:7]
	v_add_u32_e32 v1, 0x4000, v1
	v_add_u32_e32 v2, 0x4000, v2
	v_add_u32_e32 v3, 4, v3
	s_nop 2
	v_sub_f32_e32 v64, v64, v24
	v_sub_f32_e32 v65, v65, v25
	v_sub_f32_e32 v66, v66, v26
	v_sub_f32_e32 v67, v67, v27
	v_sub_f32_e32 v68, v68, v28
	v_sub_f32_e32 v69, v69, v29
	v_sub_f32_e32 v70, v70, v30
	v_sub_f32_e32 v71, v71, v31
	v_cvt_pk_bf16_f32 v64, v64, v65
	v_cvt_pk_bf16_f32 v65, v66, v67
	v_cvt_pk_bf16_f32 v68, v68, v69
	v_cvt_pk_bf16_f32 v69, v70, v71
	ds_write_b64 v10, v[64:65] offset:17408
	ds_write_b64 v10, v[68:69] offset:19712
	s_waitcnt lgkmcnt(0)
	s_barrier
	ds_read_b128 v[32:35], v9 offset:17408
	ds_read_b128 v[36:39], v9 offset:19712
	ds_read_b128 v[40:43], v9 offset:17472
	ds_read_b128 v[44:47], v9 offset:19776
	s_waitcnt lgkmcnt(2)
	v_mfma_f32_16x16x32_bf16 v[16:19], v[96:99], v[32:35], v[16:19]
	v_mfma_f32_16x16x32_bf16 v[20:23], v[96:99], v[36:39], v[20:23]
	s_waitcnt lgkmcnt(0)
	v_mfma_f32_16x16x32_bf16 v[16:19], v[100:103], v[40:43], v[16:19]
	v_mfma_f32_16x16x32_bf16 v[20:23], v[100:103], v[44:47], v[20:23]
	s_nop 7
	v_cvt_pk_bf16_f32 v64, v16, v17
	v_cvt_pk_bf16_f32 v65, v18, v19
	v_cvt_pk_bf16_f32 v66, v20, v21
	v_cvt_pk_bf16_f32 v67, v22, v23
	ds_write_b64 v11, v[64:65] offset:8704
	ds_write_b64 v11, v[66:67] offset:13056
	s_waitcnt lgkmcnt(0)
	s_barrier
	s_waitcnt vmcnt(14)
	ds_read_b128 v[32:35], v8 offset:8704
	ds_read_b128 v[36:39], v8 offset:13056
	ds_read_b128 v[40:43], v8 offset:8768
	ds_read_b128 v[44:47], v8 offset:13120
	ds_read_b128 v[48:51], v8 offset:8832
	ds_read_b128 v[52:55], v8 offset:13184
	ds_read_b128 v[56:59], v8 offset:8896
	ds_read_b128 v[60:63], v8 offset:13248
	global_load_dwordx4 v[216:219], v1, s[0:1]
	global_load_dwordx4 v[220:223], v1, s[0:1] offset:1024
	s_waitcnt vmcnt(11)
	v_mul_f32_e32 v16, v185, v16
	v_mul_f32_e32 v17, v185, v17
	v_mul_f32_e32 v18, v185, v18
	v_mul_f32_e32 v19, v185, v19
	global_load_dwordx4 v[224:227], v1, s[0:1] offset:2048
	v_mul_f32_e32 v20, v185, v20
	v_mul_f32_e32 v21, v185, v21
	v_mul_f32_e32 v22, v185, v22
	v_mul_f32_e32 v23, v185, v23
	v_lshlrev_b32_e32 v64, 16, v120
	v_and_b32_e32 v65, 0xffff0000, v120
	v_lshlrev_b32_e32 v66, 16, v121
	v_and_b32_e32 v67, 0xffff0000, v121
	v_lshlrev_b32_e32 v68, 16, v122
	v_and_b32_e32 v69, 0xffff0000, v122
	v_lshlrev_b32_e32 v70, 16, v123
	v_and_b32_e32 v71, 0xffff0000, v123
	global_load_dwordx4 v[228:231], v1, s[0:1] offset:3072
	s_waitcnt lgkmcnt(6)
	v_mfma_f32_16x16x32_bf16 v[24:27], v[104:107], v[32:35], 0
	v_mfma_f32_16x16x32_bf16 v[28:31], v[104:107], v[36:39], 0
	global_load_dwordx2 v[232:233], v2, s[2:3]
	s_waitcnt lgkmcnt(4)
	v_mfma_f32_16x16x32_bf16 v[24:27], v[108:111], v[40:43], v[24:27]
	v_mfma_f32_16x16x32_bf16 v[28:31], v[108:111], v[44:47], v[28:31]
	global_load_dwordx2 v[234:235], v2, s[2:3] offset:2048
	s_waitcnt lgkmcnt(2)
	v_mfma_f32_16x16x32_bf16 v[24:27], v[112:115], v[48:51], v[24:27]
	v_mfma_f32_16x16x32_bf16 v[28:31], v[112:115], v[52:55], v[28:31]
	global_load_dwordx4 v[240:243], v1, s[4:5]
	s_waitcnt lgkmcnt(0)
	v_mfma_f32_16x16x32_bf16 v[24:27], v[116:119], v[56:59], v[24:27]
	v_mfma_f32_16x16x32_bf16 v[28:31], v[116:119], v[60:63], v[28:31]
	global_load_dwordx4 v[244:247], v1, s[4:5] offset:1024
	global_load_dword v187, v3, s[6:7]
	v_add_u32_e32 v1, 0x4000, v1
	v_add_u32_e32 v2, 0x4000, v2
	v_add_u32_e32 v3, 4, v3
	s_nop 2
	v_sub_f32_e32 v64, v64, v24
	v_sub_f32_e32 v65, v65, v25
	v_sub_f32_e32 v66, v66, v26
	v_sub_f32_e32 v67, v67, v27
	v_sub_f32_e32 v68, v68, v28
	v_sub_f32_e32 v69, v69, v29
	v_sub_f32_e32 v70, v70, v30
	v_sub_f32_e32 v71, v71, v31
	v_cvt_pk_bf16_f32 v64, v64, v65
	v_cvt_pk_bf16_f32 v65, v66, v67
	v_cvt_pk_bf16_f32 v68, v68, v69
	v_cvt_pk_bf16_f32 v69, v70, v71
	ds_write_b64 v10, v[64:65] offset:17408
	ds_write_b64 v10, v[68:69] offset:19712
	s_waitcnt lgkmcnt(0)
	s_barrier
	ds_read_b128 v[32:35], v9 offset:17408
	ds_read_b128 v[36:39], v9 offset:19712
	ds_read_b128 v[40:43], v9 offset:17472
	ds_read_b128 v[44:47], v9 offset:19776
	s_waitcnt lgkmcnt(2)
	v_mfma_f32_16x16x32_bf16 v[16:19], v[128:131], v[32:35], v[16:19]
	v_mfma_f32_16x16x32_bf16 v[20:23], v[128:131], v[36:39], v[20:23]
	s_waitcnt lgkmcnt(0)
	v_mfma_f32_16x16x32_bf16 v[16:19], v[132:135], v[40:43], v[16:19]
	v_mfma_f32_16x16x32_bf16 v[20:23], v[132:135], v[44:47], v[20:23]
	s_nop 7
	v_cvt_pk_bf16_f32 v64, v16, v17
	v_cvt_pk_bf16_f32 v65, v18, v19
	v_cvt_pk_bf16_f32 v66, v20, v21
	v_cvt_pk_bf16_f32 v67, v22, v23
	ds_write_b64 v11, v[64:65] offset:0
	ds_write_b64 v11, v[66:67] offset:4352
	s_waitcnt lgkmcnt(0)
	s_barrier
	s_waitcnt vmcnt(14)
	ds_read_b128 v[32:35], v8 offset:0
	ds_read_b128 v[36:39], v8 offset:4352
	ds_read_b128 v[40:43], v8 offset:64
	ds_read_b128 v[44:47], v8 offset:4416
	ds_read_b128 v[48:51], v8 offset:128
	ds_read_b128 v[52:55], v8 offset:4480
	ds_read_b128 v[56:59], v8 offset:192
	ds_read_b128 v[60:63], v8 offset:4544
	global_load_dwordx4 v[72:75], v1, s[0:1]
	global_load_dwordx4 v[76:79], v1, s[0:1] offset:1024
	s_waitcnt vmcnt(11)
	v_mul_f32_e32 v16, v186, v16
	v_mul_f32_e32 v17, v186, v17
	v_mul_f32_e32 v18, v186, v18
	v_mul_f32_e32 v19, v186, v19
	global_load_dwordx4 v[80:83], v1, s[0:1] offset:2048
	v_mul_f32_e32 v20, v186, v20
	v_mul_f32_e32 v21, v186, v21
	v_mul_f32_e32 v22, v186, v22
	v_mul_f32_e32 v23, v186, v23
	v_lshlrev_b32_e32 v64, 16, v188
	v_and_b32_e32 v65, 0xffff0000, v188
	v_lshlrev_b32_e32 v66, 16, v189
	v_and_b32_e32 v67, 0xffff0000, v189
	v_lshlrev_b32_e32 v68, 16, v190
	v_and_b32_e32 v69, 0xffff0000, v190
	v_lshlrev_b32_e32 v70, 16, v191
	v_and_b32_e32 v71, 0xffff0000, v191
	global_load_dwordx4 v[84:87], v1, s[0:1] offset:3072
	s_waitcnt lgkmcnt(6)
	v_mfma_f32_16x16x32_bf16 v[24:27], v[136:139], v[32:35], 0
	v_mfma_f32_16x16x32_bf16 v[28:31], v[136:139], v[36:39], 0
	global_load_dwordx2 v[88:89], v2, s[2:3]
	s_waitcnt lgkmcnt(4)
	v_mfma_f32_16x16x32_bf16 v[24:27], v[140:143], v[40:43], v[24:27]
	v_mfma_f32_16x16x32_bf16 v[28:31], v[140:143], v[44:47], v[28:31]
	global_load_dwordx2 v[90:91], v2, s[2:3] offset:2048
	s_waitcnt lgkmcnt(2)
	v_mfma_f32_16x16x32_bf16 v[24:27], v[144:147], v[48:51], v[24:27]
	v_mfma_f32_16x16x32_bf16 v[28:31], v[144:147], v[52:55], v[28:31]
	global_load_dwordx4 v[96:99], v1, s[4:5]
	s_waitcnt lgkmcnt(0)
	v_mfma_f32_16x16x32_bf16 v[24:27], v[148:151], v[56:59], v[24:27]
	v_mfma_f32_16x16x32_bf16 v[28:31], v[148:151], v[60:63], v[28:31]
	global_load_dwordx4 v[100:103], v1, s[4:5] offset:1024
	global_load_dword v184, v3, s[6:7]
	v_add_u32_e32 v1, 0x4000, v1
	v_add_u32_e32 v2, 0x4000, v2
	v_add_u32_e32 v3, 4, v3
	s_nop 2
	v_sub_f32_e32 v64, v64, v24
	v_sub_f32_e32 v65, v65, v25
	v_sub_f32_e32 v66, v66, v26
	v_sub_f32_e32 v67, v67, v27
	v_sub_f32_e32 v68, v68, v28
	v_sub_f32_e32 v69, v69, v29
	v_sub_f32_e32 v70, v70, v30
	v_sub_f32_e32 v71, v71, v31
	v_cvt_pk_bf16_f32 v64, v64, v65
	v_cvt_pk_bf16_f32 v65, v66, v67
	v_cvt_pk_bf16_f32 v68, v68, v69
	v_cvt_pk_bf16_f32 v69, v70, v71
	ds_write_b64 v10, v[64:65] offset:17408
	ds_write_b64 v10, v[68:69] offset:19712
	s_waitcnt lgkmcnt(0)
	s_barrier
	ds_read_b128 v[32:35], v9 offset:17408
	ds_read_b128 v[36:39], v9 offset:19712
	ds_read_b128 v[40:43], v9 offset:17472
	ds_read_b128 v[44:47], v9 offset:19776
	s_waitcnt lgkmcnt(2)
	v_mfma_f32_16x16x32_bf16 v[16:19], v[196:199], v[32:35], v[16:19]
	v_mfma_f32_16x16x32_bf16 v[20:23], v[196:199], v[36:39], v[20:23]
	s_waitcnt lgkmcnt(0)
	v_mfma_f32_16x16x32_bf16 v[16:19], v[200:203], v[40:43], v[16:19]
	v_mfma_f32_16x16x32_bf16 v[20:23], v[200:203], v[44:47], v[20:23]
	s_nop 7
	v_cvt_pk_bf16_f32 v64, v16, v17
	v_cvt_pk_bf16_f32 v65, v18, v19
	v_cvt_pk_bf16_f32 v66, v20, v21
	v_cvt_pk_bf16_f32 v67, v22, v23
	ds_write_b64 v11, v[64:65] offset:8704
	ds_write_b64 v11, v[66:67] offset:13056
	s_waitcnt lgkmcnt(0)
	s_barrier
	s_waitcnt vmcnt(14)
	ds_read_b128 v[32:35], v8 offset:8704
	ds_read_b128 v[36:39], v8 offset:13056
	ds_read_b128 v[40:43], v8 offset:8768
	ds_read_b128 v[44:47], v8 offset:13120
	ds_read_b128 v[48:51], v8 offset:8832
	ds_read_b128 v[52:55], v8 offset:13184
	ds_read_b128 v[56:59], v8 offset:8896
	ds_read_b128 v[60:63], v8 offset:13248
	global_load_dwordx4 v[104:107], v1, s[0:1]
	global_load_dwordx4 v[108:111], v1, s[0:1] offset:1024
	s_waitcnt vmcnt(11)
	v_mul_f32_e32 v16, v187, v16
	v_mul_f32_e32 v17, v187, v17
	v_mul_f32_e32 v18, v187, v18
	v_mul_f32_e32 v19, v187, v19
	global_load_dwordx4 v[112:115], v1, s[0:1] offset:2048
	v_mul_f32_e32 v20, v187, v20
	v_mul_f32_e32 v21, v187, v21
	v_mul_f32_e32 v22, v187, v22
	v_mul_f32_e32 v23, v187, v23
	v_lshlrev_b32_e32 v64, 16, v232
	v_and_b32_e32 v65, 0xffff0000, v232
	v_lshlrev_b32_e32 v66, 16, v233
	v_and_b32_e32 v67, 0xffff0000, v233
	v_lshlrev_b32_e32 v68, 16, v234
	v_and_b32_e32 v69, 0xffff0000, v234
	v_lshlrev_b32_e32 v70, 16, v235
	v_and_b32_e32 v71, 0xffff0000, v235
	global_load_dwordx4 v[116:119], v1, s[0:1] offset:3072
	s_waitcnt lgkmcnt(6)
	v_mfma_f32_16x16x32_bf16 v[24:27], v[216:219], v[32:35], 0
	v_mfma_f32_16x16x32_bf16 v[28:31], v[216:219], v[36:39], 0
	global_load_dwordx2 v[120:121], v2, s[2:3]
	s_waitcnt lgkmcnt(4)
	v_mfma_f32_16x16x32_bf16 v[24:27], v[220:223], v[40:43], v[24:27]
	v_mfma_f32_16x16x32_bf16 v[28:31], v[220:223], v[44:47], v[28:31]
	global_load_dwordx2 v[122:123], v2, s[2:3] offset:2048
	s_waitcnt lgkmcnt(2)
	v_mfma_f32_16x16x32_bf16 v[24:27], v[224:227], v[48:51], v[24:27]
	v_mfma_f32_16x16x32_bf16 v[28:31], v[224:227], v[52:55], v[28:31]
	global_load_dwordx4 v[128:131], v1, s[4:5]
	s_waitcnt lgkmcnt(0)
	v_mfma_f32_16x16x32_bf16 v[24:27], v[228:231], v[56:59], v[24:27]
	v_mfma_f32_16x16x32_bf16 v[28:31], v[228:231], v[60:63], v[28:31]
	global_load_dwordx4 v[132:135], v1, s[4:5] offset:1024
	global_load_dword v185, v3, s[6:7]
	v_add_u32_e32 v1, 0x4000, v1
	v_add_u32_e32 v2, 0x4000, v2
	v_add_u32_e32 v3, 4, v3
	s_nop 2
	v_sub_f32_e32 v64, v64, v24
	v_sub_f32_e32 v65, v65, v25
	v_sub_f32_e32 v66, v66, v26
	v_sub_f32_e32 v67, v67, v27
	v_sub_f32_e32 v68, v68, v28
	v_sub_f32_e32 v69, v69, v29
	v_sub_f32_e32 v70, v70, v30
	v_sub_f32_e32 v71, v71, v31
	v_cvt_pk_bf16_f32 v64, v64, v65
	v_cvt_pk_bf16_f32 v65, v66, v67
	v_cvt_pk_bf16_f32 v68, v68, v69
	v_cvt_pk_bf16_f32 v69, v70, v71
	ds_write_b64 v10, v[64:65] offset:17408
	ds_write_b64 v10, v[68:69] offset:19712
	s_waitcnt lgkmcnt(0)
	s_barrier
	ds_read_b128 v[32:35], v9 offset:17408
	ds_read_b128 v[36:39], v9 offset:19712
	ds_read_b128 v[40:43], v9 offset:17472
	ds_read_b128 v[44:47], v9 offset:19776
	s_waitcnt lgkmcnt(2)
	v_mfma_f32_16x16x32_bf16 v[16:19], v[240:243], v[32:35], v[16:19]
	v_mfma_f32_16x16x32_bf16 v[20:23], v[240:243], v[36:39], v[20:23]
	s_waitcnt lgkmcnt(0)
	v_mfma_f32_16x16x32_bf16 v[16:19], v[244:247], v[40:43], v[16:19]
	v_mfma_f32_16x16x32_bf16 v[20:23], v[244:247], v[44:47], v[20:23]
	s_nop 7
	v_cvt_pk_bf16_f32 v64, v16, v17
	v_cvt_pk_bf16_f32 v65, v18, v19
	v_cvt_pk_bf16_f32 v66, v20, v21
	v_cvt_pk_bf16_f32 v67, v22, v23
	ds_write_b64 v11, v[64:65] offset:0
	ds_write_b64 v11, v[66:67] offset:4352
	s_waitcnt lgkmcnt(0)
	s_barrier
	s_sub_u32 s10, s10, 1
	s_cmp_lg_u32 s10, 0
	s_cbranch_scc1 .Lscan_V_loop
	s_branch .Lscan_done
.Lscan_O_path:
	v_lshlrev_b32_e32 v2, 4, v14
	global_load_dwordx4 v[72:75], v1, s[0:1]
	global_load_dwordx4 v[76:79], v1, s[0:1] offset:1024
	global_load_dwordx4 v[80:83], v1, s[0:1] offset:2048
	global_load_dwordx4 v[84:87], v1, s[0:1] offset:3072
	global_load_dwordx4 v[88:91], v2, s[2:3]
	global_load_dwordx4 v[92:95], v2, s[2:3] offset:1024
	global_load_dwordx4 v[96:99], v1, s[4:5]
	global_load_dwordx4 v[100:103], v1, s[4:5] offset:1024
	global_load_dword v184, v3, s[6:7]
	v_add_u32_e32 v1, 0x4000, v1
	v_add_u32_e32 v2, 0x2000, v2
	v_add_u32_e32 v3, 4, v3
	global_load_dwordx4 v[104:107], v1, s[0:1]
	global_load_dwordx4 v[108:111], v1, s[0:1] offset:1024
	global_load_dwordx4 v[112:115], v1, s[0:1] offset:2048
	global_load_dwordx4 v[116:119], v1, s[0:1] offset:3072
	global_load_dwordx4 v[120:123], v2, s[2:3]
	global_load_dwordx4 v[124:127], v2, s[2:3] offset:1024
	global_load_dwordx4 v[128:131], v1, s[4:5]
	global_load_dwordx4 v[132:135], v1, s[4:5] offset:1024
	global_load_dword v185, v3, s[6:7]
	v_add_u32_e32 v1, 0x4000, v1
	v_add_u32_e32 v2, 0x2000, v2
	v_add_u32_e32 v3, 4, v3
	s_waitcnt vmcnt(0)
	s_movk_i32 s10, 32
.Lscan_O_loop:
	s_waitcnt vmcnt(16)
	ds_read_b128 v[32:35], v8 offset:0
	ds_read_b128 v[36:39], v8 offset:4352
	ds_read_b128 v[40:43], v8 offset:64
	ds_read_b128 v[44:47], v8 offset:4416
	ds_read_b128 v[48:51], v8 offset:128
	ds_read_b128 v[52:55], v8 offset:4480
	ds_read_b128 v[56:59], v8 offset:192
	ds_read_b128 v[60:63], v8 offset:4544
	global_load_dwordx4 v[136:139], v1, s[0:1]
	global_load_dwordx4 v[140:143], v1, s[0:1] offset:1024
	s_waitcnt vmcnt(13)
	v_mul_f32_e32 v16, v184, v16
	v_mul_f32_e32 v17, v184, v17
	v_mul_f32_e32 v18, v184, v18
	v_mul_f32_e32 v19, v184, v19
	global_load_dwordx4 v[144:147], v1, s[0:1] offset:2048
	v_mul_f32_e32 v20, v184, v20
	v_mul_f32_e32 v21, v184, v21
	v_mul_f32_e32 v22, v184, v22
	v_mul_f32_e32 v23, v184, v23
	global_load_dwordx4 v[148:151], v1, s[0:1] offset:3072
	s_waitcnt lgkmcnt(6)
	v_mfma_f32_16x16x32_bf16 v[24:27], v[72:75], v[32:35], 0
	v_mfma_f32_16x16x32_bf16 v[28:31], v[72:75], v[36:39], 0
	global_load_dwordx4 v[188:191], v2, s[2:3]
	s_waitcnt lgkmcnt(4)
	v_mfma_f32_16x16x32_bf16 v[24:27], v[76:79], v[40:43], v[24:27]
	v_mfma_f32_16x16x32_bf16 v[28:31], v[76:79], v[44:47], v[28:31]
	global_load_dwordx4 v[192:195], v2, s[2:3] offset:1024
	s_waitcnt lgkmcnt(2)
	v_mfma_f32_16x16x32_bf16 v[24:27], v[80:83], v[48:51], v[24:27]
	v_mfma_f32_16x16x32_bf16 v[28:31], v[80:83], v[52:55], v[28:31]
	global_load_dwordx4 v[196:199], v1, s[4:5]
	s_waitcnt lgkmcnt(0)
	v_mfma_f32_16x16x32_bf16 v[24:27], v[84:87], v[56:59], v[24:27]
	v_mfma_f32_16x16x32_bf16 v[28:31], v[84:87], v[60:63], v[28:31]
	global_load_dwordx4 v[200:203], v1, s[4:5] offset:1024
	global_load_dword v186, v3, s[6:7]
	v_add_u32_e32 v1, 0x4000, v1
	v_add_u32_e32 v2, 0x2000, v2
	v_add_u32_e32 v3, 4, v3
	s_waitcnt lgkmcnt(0)
	s_barrier
	ds_read_b128 v[32:35], v9 offset:17408
	ds_read_b128 v[36:39], v9 offset:19712
	ds_read_b128 v[40:43], v9 offset:17472
	ds_read_b128 v[44:47], v9 offset:19776
	s_waitcnt lgkmcnt(2)
	v_mfma_f32_16x16x32_bf16 v[16:19], v[96:99], v[32:35], v[16:19]
	v_mfma_f32_16x16x32_bf16 v[20:23], v[96:99], v[36:39], v[20:23]
	v_mfma_f32_16x16x32_bf16 v[24:27], v[88:91], v[32:35], v[24:27]
	v_mfma_f32_16x16x32_bf16 v[28:31], v[88:91], v[36:39], v[28:31]
	s_waitcnt lgkmcnt(0)
	v_mfma_f32_16x16x32_bf16 v[16:19], v[100:103], v[40:43], v[16:19]
	v_mfma_f32_16x16x32_bf16 v[20:23], v[100:103], v[44:47], v[20:23]
	v_mfma_f32_16x16x32_bf16 v[24:27], v[92:95], v[40:43], v[24:27]
	v_mfma_f32_16x16x32_bf16 v[28:31], v[92:95], v[44:47], v[28:31]
	s_nop 5
	v_cvt_pk_bf16_f32 v64, v16, v17
	v_cvt_pk_bf16_f32 v65, v18, v19
	v_cvt_pk_bf16_f32 v66, v20, v21
	v_cvt_pk_bf16_f32 v67, v22, v23
	ds_write_b64 v11, v[64:65] offset:8704
	ds_write_b64 v11, v[66:67] offset:13056
	v_cvt_pk_bf16_f32 v68, v24, v25
	v_cvt_pk_bf16_f32 v69, v26, v27
	v_cvt_pk_bf16_f32 v70, v28, v29
	v_cvt_pk_bf16_f32 v71, v30, v31
	ds_write_b16 v13, v68 offset:0
	ds_write_b16_d16_hi v13, v68 offset:80
	ds_write_b16 v13, v69 offset:160
	ds_write_b16_d16_hi v13, v69 offset:240
	ds_write_b16 v13, v70 offset:32
	ds_write_b16_d16_hi v13, v70 offset:112
	ds_write_b16 v13, v71 offset:192
	ds_write_b16_d16_hi v13, v71 offset:272
	ds_read_b128 v[176:179], v172
	s_waitcnt lgkmcnt(0)
	s_barrier
	global_store_dwordx4 v12, v[176:179], s[8:9]
	v_add_u32_e32 v12, 0x20000, v12
	s_waitcnt vmcnt(16)
	ds_read_b128 v[32:35], v8 offset:8704
	ds_read_b128 v[36:39], v8 offset:13056
	ds_read_b128 v[40:43], v8 offset:8768
	ds_read_b128 v[44:47], v8 offset:13120
	ds_read_b128 v[48:51], v8 offset:8832
	ds_read_b128 v[52:55], v8 offset:13184
	ds_read_b128 v[56:59], v8 offset:8896
	ds_read_b128 v[60:63], v8 offset:13248
	global_load_dwordx4 v[216:219], v1, s[0:1]
	global_load_dwordx4 v[220:223], v1, s[0:1] offset:1024
	s_waitcnt vmcnt(13)
	v_mul_f32_e32 v16, v185, v16
	v_mul_f32_e32 v17, v185, v17
	v_mul_f32_e32 v18, v185, v18
	v_mul_f32_e32 v19, v185, v19
	global_load_dwordx4 v[224:227], v1, s[0:1] offset:2048
	v_mul_f32_e32 v20, v185, v20
	v_mul_f32_e32 v21, v185, v21
	v_mul_f32_e32 v22, v185, v22
	v_mul_f32_e32 v23, v185, v23
	global_load_dwordx4 v[228:231], v1, s[0:1] offset:3072
	s_waitcnt lgkmcnt(6)
	v_mfma_f32_16x16x32_bf16 v[24:27], v[104:107], v[32:35], 0
	v_mfma_f32_16x16x32_bf16 v[28:31], v[104:107], v[36:39], 0
	global_load_dwordx4 v[232:235], v2, s[2:3]
	s_waitcnt lgkmcnt(4)
	v_mfma_f32_16x16x32_bf16 v[24:27], v[108:111], v[40:43], v[24:27]
	v_mfma_f32_16x16x32_bf16 v[28:31], v[108:111], v[44:47], v[28:31]
	global_load_dwordx4 v[236:239], v2, s[2:3] offset:1024
	s_waitcnt lgkmcnt(2)
	v_mfma_f32_16x16x32_bf16 v[24:27], v[112:115], v[48:51], v[24:27]
	v_mfma_f32_16x16x32_bf16 v[28:31], v[112:115], v[52:55], v[28:31]
	global_load_dwordx4 v[240:243], v1, s[4:5]
	s_waitcnt lgkmcnt(0)
	v_mfma_f32_16x16x32_bf16 v[24:27], v[116:119], v[56:59], v[24:27]
	v_mfma_f32_16x16x32_bf16 v[28:31], v[116:119], v[60:63], v[28:31]
	global_load_dwordx4 v[244:247], v1, s[4:5] offset:1024
	global_load_dword v187, v3, s[6:7]
	v_add_u32_e32 v1, 0x4000, v1
	v_add_u32_e32 v2, 0x2000, v2
	v_add_u32_e32 v3, 4, v3
	s_waitcnt lgkmcnt(0)
	s_barrier
	ds_read_b128 v[32:35], v9 offset:17408
	ds_read_b128 v[36:39], v9 offset:19712
	ds_read_b128 v[40:43], v9 offset:17472
	ds_read_b128 v[44:47], v9 offset:19776
	s_waitcnt lgkmcnt(2)
	v_mfma_f32_16x16x32_bf16 v[16:19], v[128:131], v[32:35], v[16:19]
	v_mfma_f32_16x16x32_bf16 v[20:23], v[128:131], v[36:39], v[20:23]
	v_mfma_f32_16x16x32_bf16 v[24:27], v[120:123], v[32:35], v[24:27]
	v_mfma_f32_16x16x32_bf16 v[28:31], v[120:123], v[36:39], v[28:31]
	s_waitcnt lgkmcnt(0)
	v_mfma_f32_16x16x32_bf16 v[16:19], v[132:135], v[40:43], v[16:19]
	v_mfma_f32_16x16x32_bf16 v[20:23], v[132:135], v[44:47], v[20:23]
	v_mfma_f32_16x16x32_bf16 v[24:27], v[124:127], v[40:43], v[24:27]
	v_mfma_f32_16x16x32_bf16 v[28:31], v[124:127], v[44:47], v[28:31]
	s_nop 5
	v_cvt_pk_bf16_f32 v64, v16, v17
	v_cvt_pk_bf16_f32 v65, v18, v19
	v_cvt_pk_bf16_f32 v66, v20, v21
	v_cvt_pk_bf16_f32 v67, v22, v23
	ds_write_b64 v11, v[64:65] offset:0
	ds_write_b64 v11, v[66:67] offset:4352
	v_cvt_pk_bf16_f32 v68, v24, v25
	v_cvt_pk_bf16_f32 v69, v26, v27
	v_cvt_pk_bf16_f32 v70, v28, v29
	v_cvt_pk_bf16_f32 v71, v30, v31
	ds_write_b16 v13, v68 offset:0
	ds_write_b16_d16_hi v13, v68 offset:80
	ds_write_b16 v13, v69 offset:160
	ds_write_b16_d16_hi v13, v69 offset:240
	ds_write_b16 v13, v70 offset:32
	ds_write_b16_d16_hi v13, v70 offset:112
	ds_write_b16 v13, v71 offset:192
	ds_write_b16_d16_hi v13, v71 offset:272
	ds_read_b128 v[176:179], v172
	s_waitcnt lgkmcnt(0)
	s_barrier
	global_store_dwordx4 v12, v[176:179], s[8:9]
	v_add_u32_e32 v12, 0x20000, v12
	s_waitcnt vmcnt(16)
	ds_read_b128 v[32:35], v8 offset:0
	ds_read_b128 v[36:39], v8 offset:4352
	ds_read_b128 v[40:43], v8 offset:64
	ds_read_b128 v[44:47], v8 offset:4416
	ds_read_b128 v[48:51], v8 offset:128
	ds_read_b128 v[52:55], v8 offset:4480
	ds_read_b128 v[56:59], v8 offset:192
	ds_read_b128 v[60:63], v8 offset:4544
	global_load_dwordx4 v[72:75], v1, s[0:1]
	global_load_dwordx4 v[76:79], v1, s[0:1] offset:1024
	s_waitcnt vmcnt(13)
	v_mul_f32_e32 v16, v186, v16
	v_mul_f32_e32 v17, v186, v17
	v_mul_f32_e32 v18, v186, v18
	v_mul_f32_e32 v19, v186, v19
	global_load_dwordx4 v[80:83], v1, s[0:1] offset:2048
	v_mul_f32_e32 v20, v186, v20
	v_mul_f32_e32 v21, v186, v21
	v_mul_f32_e32 v22, v186, v22
	v_mul_f32_e32 v23, v186, v23
	global_load_dwordx4 v[84:87], v1, s[0:1] offset:3072
	s_waitcnt lgkmcnt(6)
	v_mfma_f32_16x16x32_bf16 v[24:27], v[136:139], v[32:35], 0
	v_mfma_f32_16x16x32_bf16 v[28:31], v[136:139], v[36:39], 0
	global_load_dwordx4 v[88:91], v2, s[2:3]
	s_waitcnt lgkmcnt(4)
	v_mfma_f32_16x16x32_bf16 v[24:27], v[140:143], v[40:43], v[24:27]
	v_mfma_f32_16x16x32_bf16 v[28:31], v[140:143], v[44:47], v[28:31]
	global_load_dwordx4 v[92:95], v2, s[2:3] offset:1024
	s_waitcnt lgkmcnt(2)
	v_mfma_f32_16x16x32_bf16 v[24:27], v[144:147], v[48:51], v[24:27]
	v_mfma_f32_16x16x32_bf16 v[28:31], v[144:147], v[52:55], v[28:31]
	global_load_dwordx4 v[96:99], v1, s[4:5]
	s_waitcnt lgkmcnt(0)
	v_mfma_f32_16x16x32_bf16 v[24:27], v[148:151], v[56:59], v[24:27]
	v_mfma_f32_16x16x32_bf16 v[28:31], v[148:151], v[60:63], v[28:31]
	global_load_dwordx4 v[100:103], v1, s[4:5] offset:1024
	global_load_dword v184, v3, s[6:7]
	v_add_u32_e32 v1, 0x4000, v1
	v_add_u32_e32 v2, 0x2000, v2
	v_add_u32_e32 v3, 4, v3
	s_waitcnt lgkmcnt(0)
	s_barrier
	ds_read_b128 v[32:35], v9 offset:17408
	ds_read_b128 v[36:39], v9 offset:19712
	ds_read_b128 v[40:43], v9 offset:17472
	ds_read_b128 v[44:47], v9 offset:19776
	s_waitcnt lgkmcnt(2)
	v_mfma_f32_16x16x32_bf16 v[16:19], v[196:199], v[32:35], v[16:19]
	v_mfma_f32_16x16x32_bf16 v[20:23], v[196:199], v[36:39], v[20:23]
	v_mfma_f32_16x16x32_bf16 v[24:27], v[188:191], v[32:35], v[24:27]
	v_mfma_f32_16x16x32_bf16 v[28:31], v[188:191], v[36:39], v[28:31]
	s_waitcnt lgkmcnt(0)
	v_mfma_f32_16x16x32_bf16 v[16:19], v[200:203], v[40:43], v[16:19]
	v_mfma_f32_16x16x32_bf16 v[20:23], v[200:203], v[44:47], v[20:23]
	v_mfma_f32_16x16x32_bf16 v[24:27], v[192:195], v[40:43], v[24:27]
	v_mfma_f32_16x16x32_bf16 v[28:31], v[192:195], v[44:47], v[28:31]
	s_nop 5
	v_cvt_pk_bf16_f32 v64, v16, v17
	v_cvt_pk_bf16_f32 v65, v18, v19
	v_cvt_pk_bf16_f32 v66, v20, v21
	v_cvt_pk_bf16_f32 v67, v22, v23
	ds_write_b64 v11, v[64:65] offset:8704
	ds_write_b64 v11, v[66:67] offset:13056
	v_cvt_pk_bf16_f32 v68, v24, v25
	v_cvt_pk_bf16_f32 v69, v26, v27
	v_cvt_pk_bf16_f32 v70, v28, v29
	v_cvt_pk_bf16_f32 v71, v30, v31
	ds_write_b16 v13, v68 offset:0
	ds_write_b16_d16_hi v13, v68 offset:80
	ds_write_b16 v13, v69 offset:160
	ds_write_b16_d16_hi v13, v69 offset:240
	ds_write_b16 v13, v70 offset:32
	ds_write_b16_d16_hi v13, v70 offset:112
	ds_write_b16 v13, v71 offset:192
	ds_write_b16_d16_hi v13, v71 offset:272
	ds_read_b128 v[176:179], v172
	s_waitcnt lgkmcnt(0)
	s_barrier
	global_store_dwordx4 v12, v[176:179], s[8:9]
	v_add_u32_e32 v12, 0x20000, v12
	s_waitcnt vmcnt(16)
	ds_read_b128 v[32:35], v8 offset:8704
	ds_read_b128 v[36:39], v8 offset:13056
	ds_read_b128 v[40:43], v8 offset:8768
	ds_read_b128 v[44:47], v8 offset:13120
	ds_read_b128 v[48:51], v8 offset:8832
	ds_read_b128 v[52:55], v8 offset:13184
	ds_read_b128 v[56:59], v8 offset:8896
	ds_read_b128 v[60:63], v8 offset:13248
	global_load_dwordx4 v[104:107], v1, s[0:1]
	global_load_dwordx4 v[108:111], v1, s[0:1] offset:1024
	s_waitcnt vmcnt(13)
	v_mul_f32_e32 v16, v187, v16
	v_mul_f32_e32 v17, v187, v17
	v_mul_f32_e32 v18, v187, v18
	v_mul_f32_e32 v19, v187, v19
	global_load_dwordx4 v[112:115], v1, s[0:1] offset:2048
	v_mul_f32_e32 v20, v187, v20
	v_mul_f32_e32 v21, v187, v21
	v_mul_f32_e32 v22, v187, v22
	v_mul_f32_e32 v23, v187, v23
	global_load_dwordx4 v[116:119], v1, s[0:1] offset:3072
	s_waitcnt lgkmcnt(6)
	v_mfma_f32_16x16x32_bf16 v[24:27], v[216:219], v[32:35], 0
	v_mfma_f32_16x16x32_bf16 v[28:31], v[216:219], v[36:39], 0
	global_load_dwordx4 v[120:123], v2, s[2:3]
	s_waitcnt lgkmcnt(4)
	v_mfma_f32_16x16x32_bf16 v[24:27], v[220:223], v[40:43], v[24:27]
	v_mfma_f32_16x16x32_bf16 v[28:31], v[220:223], v[44:47], v[28:31]
	global_load_dwordx4 v[124:127], v2, s[2:3] offset:1024
	s_waitcnt lgkmcnt(2)
	v_mfma_f32_16x16x32_bf16 v[24:27], v[224:227], v[48:51], v[24:27]
	v_mfma_f32_16x16x32_bf16 v[28:31], v[224:227], v[52:55], v[28:31]
	global_load_dwordx4 v[128:131], v1, s[4:5]
	s_waitcnt lgkmcnt(0)
	v_mfma_f32_16x16x32_bf16 v[24:27], v[228:231], v[56:59], v[24:27]
	v_mfma_f32_16x16x32_bf16 v[28:31], v[228:231], v[60:63], v[28:31]
	global_load_dwordx4 v[132:135], v1, s[4:5] offset:1024
	global_load_dword v185, v3, s[6:7]
	v_add_u32_e32 v1, 0x4000, v1
	v_add_u32_e32 v2, 0x2000, v2
	v_add_u32_e32 v3, 4, v3
	s_waitcnt lgkmcnt(0)
	s_barrier
	ds_read_b128 v[32:35], v9 offset:17408
	ds_read_b128 v[36:39], v9 offset:19712
	ds_read_b128 v[40:43], v9 offset:17472
	ds_read_b128 v[44:47], v9 offset:19776
	s_waitcnt lgkmcnt(2)
	v_mfma_f32_16x16x32_bf16 v[16:19], v[240:243], v[32:35], v[16:19]
	v_mfma_f32_16x16x32_bf16 v[20:23], v[240:243], v[36:39], v[20:23]
	v_mfma_f32_16x16x32_bf16 v[24:27], v[232:235], v[32:35], v[24:27]
	v_mfma_f32_16x16x32_bf16 v[28:31], v[232:235], v[36:39], v[28:31]
	s_waitcnt lgkmcnt(0)
	v_mfma_f32_16x16x32_bf16 v[16:19], v[244:247], v[40:43], v[16:19]
	v_mfma_f32_16x16x32_bf16 v[20:23], v[244:247], v[44:47], v[20:23]
	v_mfma_f32_16x16x32_bf16 v[24:27], v[236:239], v[40:43], v[24:27]
	v_mfma_f32_16x16x32_bf16 v[28:31], v[236:239], v[44:47], v[28:31]
	s_nop 5
	v_cvt_pk_bf16_f32 v64, v16, v17
	v_cvt_pk_bf16_f32 v65, v18, v19
	v_cvt_pk_bf16_f32 v66, v20, v21
	v_cvt_pk_bf16_f32 v67, v22, v23
	ds_write_b64 v11, v[64:65] offset:0
	ds_write_b64 v11, v[66:67] offset:4352
	v_cvt_pk_bf16_f32 v68, v24, v25
	v_cvt_pk_bf16_f32 v69, v26, v27
	v_cvt_pk_bf16_f32 v70, v28, v29
	v_cvt_pk_bf16_f32 v71, v30, v31
	ds_write_b16 v13, v68 offset:0
	ds_write_b16_d16_hi v13, v68 offset:80
	ds_write_b16 v13, v69 offset:160
	ds_write_b16_d16_hi v13, v69 offset:240
	ds_write_b16 v13, v70 offset:32
	ds_write_b16_d16_hi v13, v70 offset:112
	ds_write_b16 v13, v71 offset:192
	ds_write_b16_d16_hi v13, v71 offset:272
	ds_read_b128 v[176:179], v172
	s_waitcnt lgkmcnt(0)
	s_barrier
	global_store_dwordx4 v12, v[176:179], s[8:9]
	v_add_u32_e32 v12, 0x20000, v12
	s_sub_u32 s10, s10, 1
	s_cmp_lg_u32 s10, 0
	s_cbranch_scc1 .Lscan_O_loop
